# prep-phase weight transpose: 32 row loads in flight per item with counted waits (was 32 serialized round trips)
# speedup vs baseline: 1.0343x; 1.0107x over previous
.LBB0_636:
	global_load_dword v78, v[0:1], off
	v_lshl_add_u64 v[0:1], v[0:1], 0, s[10:11]
	global_load_dword v79, v[0:1], off
	v_lshl_add_u64 v[0:1], v[0:1], 0, s[10:11]
	global_load_dword v80, v[0:1], off
	v_lshl_add_u64 v[0:1], v[0:1], 0, s[10:11]
	global_load_dword v81, v[0:1], off
	v_lshl_add_u64 v[0:1], v[0:1], 0, s[10:11]
	global_load_dword v82, v[0:1], off
	v_lshl_add_u64 v[0:1], v[0:1], 0, s[10:11]
	global_load_dword v83, v[0:1], off
	v_lshl_add_u64 v[0:1], v[0:1], 0, s[10:11]
	global_load_dword v84, v[0:1], off
	v_lshl_add_u64 v[0:1], v[0:1], 0, s[10:11]
	global_load_dword v85, v[0:1], off
	v_lshl_add_u64 v[0:1], v[0:1], 0, s[10:11]
	global_load_dword v86, v[0:1], off
	v_lshl_add_u64 v[0:1], v[0:1], 0, s[10:11]
	global_load_dword v87, v[0:1], off
	v_lshl_add_u64 v[0:1], v[0:1], 0, s[10:11]
	global_load_dword v88, v[0:1], off
	v_lshl_add_u64 v[0:1], v[0:1], 0, s[10:11]
	global_load_dword v89, v[0:1], off
	v_lshl_add_u64 v[0:1], v[0:1], 0, s[10:11]
	global_load_dword v90, v[0:1], off
	v_lshl_add_u64 v[0:1], v[0:1], 0, s[10:11]
	global_load_dword v91, v[0:1], off
	v_lshl_add_u64 v[0:1], v[0:1], 0, s[10:11]
	global_load_dword v92, v[0:1], off
	v_lshl_add_u64 v[0:1], v[0:1], 0, s[10:11]
	global_load_dword v93, v[0:1], off
	v_lshl_add_u64 v[0:1], v[0:1], 0, s[10:11]
	global_load_dword v94, v[0:1], off
	v_lshl_add_u64 v[0:1], v[0:1], 0, s[10:11]
	global_load_dword v95, v[0:1], off
	v_lshl_add_u64 v[0:1], v[0:1], 0, s[10:11]
	global_load_dword v96, v[0:1], off
	v_lshl_add_u64 v[0:1], v[0:1], 0, s[10:11]
	global_load_dword v97, v[0:1], off
	v_lshl_add_u64 v[0:1], v[0:1], 0, s[10:11]
	global_load_dword v98, v[0:1], off
	v_lshl_add_u64 v[0:1], v[0:1], 0, s[10:11]
	global_load_dword v99, v[0:1], off
	v_lshl_add_u64 v[0:1], v[0:1], 0, s[10:11]
	global_load_dword v100, v[0:1], off
	v_lshl_add_u64 v[0:1], v[0:1], 0, s[10:11]
	global_load_dword v101, v[0:1], off
	v_lshl_add_u64 v[0:1], v[0:1], 0, s[10:11]
	global_load_dword v102, v[0:1], off
	v_lshl_add_u64 v[0:1], v[0:1], 0, s[10:11]
	global_load_dword v103, v[0:1], off
	v_lshl_add_u64 v[0:1], v[0:1], 0, s[10:11]
	global_load_dword v104, v[0:1], off
	v_lshl_add_u64 v[0:1], v[0:1], 0, s[10:11]
	global_load_dword v105, v[0:1], off
	v_lshl_add_u64 v[0:1], v[0:1], 0, s[10:11]
	global_load_dword v106, v[0:1], off
	v_lshl_add_u64 v[0:1], v[0:1], 0, s[10:11]
	global_load_dword v107, v[0:1], off
	v_lshl_add_u64 v[0:1], v[0:1], 0, s[10:11]
	global_load_dword v108, v[0:1], off
	v_lshl_add_u64 v[0:1], v[0:1], 0, s[10:11]
	global_load_dword v109, v[0:1], off
	v_lshl_add_u64 v[0:1], v[0:1], 0, s[10:11]
	s_waitcnt vmcnt(31)
	v_cndmask_b32_e32 v78, 0, v78, vcc
	ds_write_b32 v9, v78
	s_waitcnt vmcnt(30)
	v_cndmask_b32_e32 v79, 0, v79, vcc
	ds_write_b32 v9, v79 offset:264
	s_waitcnt vmcnt(29)
	v_cndmask_b32_e32 v80, 0, v80, vcc
	ds_write_b32 v9, v80 offset:528
	s_waitcnt vmcnt(28)
	v_cndmask_b32_e32 v81, 0, v81, vcc
	ds_write_b32 v9, v81 offset:792
	s_waitcnt vmcnt(27)
	v_cndmask_b32_e32 v82, 0, v82, vcc
	ds_write_b32 v9, v82 offset:1056
	s_waitcnt vmcnt(26)
	v_cndmask_b32_e32 v83, 0, v83, vcc
	ds_write_b32 v9, v83 offset:1320
	s_waitcnt vmcnt(25)
	v_cndmask_b32_e32 v84, 0, v84, vcc
	ds_write_b32 v9, v84 offset:1584
	s_waitcnt vmcnt(24)
	v_cndmask_b32_e32 v85, 0, v85, vcc
	ds_write_b32 v9, v85 offset:1848
	s_waitcnt vmcnt(23)
	v_cndmask_b32_e32 v86, 0, v86, vcc
	ds_write_b32 v9, v86 offset:2112
	s_waitcnt vmcnt(22)
	v_cndmask_b32_e32 v87, 0, v87, vcc
	ds_write_b32 v9, v87 offset:2376
	s_waitcnt vmcnt(21)
	v_cndmask_b32_e32 v88, 0, v88, vcc
	ds_write_b32 v9, v88 offset:2640
	s_waitcnt vmcnt(20)
	v_cndmask_b32_e32 v89, 0, v89, vcc
	ds_write_b32 v9, v89 offset:2904
	s_waitcnt vmcnt(19)
	v_cndmask_b32_e32 v90, 0, v90, vcc
	ds_write_b32 v9, v90 offset:3168
	s_waitcnt vmcnt(18)
	v_cndmask_b32_e32 v91, 0, v91, vcc
	ds_write_b32 v9, v91 offset:3432
	s_waitcnt vmcnt(17)
	v_cndmask_b32_e32 v92, 0, v92, vcc
	ds_write_b32 v9, v92 offset:3696
	s_waitcnt vmcnt(16)
	v_cndmask_b32_e32 v93, 0, v93, vcc
	ds_write_b32 v9, v93 offset:3960
	s_waitcnt vmcnt(15)
	v_cndmask_b32_e32 v94, 0, v94, vcc
	ds_write_b32 v9, v94 offset:4224
	s_waitcnt vmcnt(14)
	v_cndmask_b32_e32 v95, 0, v95, vcc
	ds_write_b32 v9, v95 offset:4488
	s_waitcnt vmcnt(13)
	v_cndmask_b32_e32 v96, 0, v96, vcc
	ds_write_b32 v9, v96 offset:4752
	s_waitcnt vmcnt(12)
	v_cndmask_b32_e32 v97, 0, v97, vcc
	ds_write_b32 v9, v97 offset:5016
	s_waitcnt vmcnt(11)
	v_cndmask_b32_e32 v98, 0, v98, vcc
	ds_write_b32 v9, v98 offset:5280
	s_waitcnt vmcnt(10)
	v_cndmask_b32_e32 v99, 0, v99, vcc
	ds_write_b32 v9, v99 offset:5544
	s_waitcnt vmcnt(9)
	v_cndmask_b32_e32 v100, 0, v100, vcc
	ds_write_b32 v9, v100 offset:5808
	s_waitcnt vmcnt(8)
	v_cndmask_b32_e32 v101, 0, v101, vcc
	ds_write_b32 v9, v101 offset:6072
	s_waitcnt vmcnt(7)
	v_cndmask_b32_e32 v102, 0, v102, vcc
	ds_write_b32 v9, v102 offset:6336
	s_waitcnt vmcnt(6)
	v_cndmask_b32_e32 v103, 0, v103, vcc
	ds_write_b32 v9, v103 offset:6600
	s_waitcnt vmcnt(5)
	v_cndmask_b32_e32 v104, 0, v104, vcc
	ds_write_b32 v9, v104 offset:6864
	s_waitcnt vmcnt(4)
	v_cndmask_b32_e32 v105, 0, v105, vcc
	ds_write_b32 v9, v105 offset:7128
	s_waitcnt vmcnt(3)
	v_cndmask_b32_e32 v106, 0, v106, vcc
	ds_write_b32 v9, v106 offset:7392
	s_waitcnt vmcnt(2)
	v_cndmask_b32_e32 v107, 0, v107, vcc
	ds_write_b32 v9, v107 offset:7656
	s_waitcnt vmcnt(1)
	v_cndmask_b32_e32 v108, 0, v108, vcc
	ds_write_b32 v9, v108 offset:7920
	s_waitcnt vmcnt(0)
	v_cndmask_b32_e32 v109, 0, v109, vcc
	ds_write_b32 v9, v109 offset:8184
	s_movk_i32 s1, 0x2100
	s_ashr_i32 s1, s0, 31
	ds_read_b32 v10, v5
	ds_read_b32 v11, v5 offset:132
	ds_read_b32 v12, v5 offset:264
	ds_read_b32 v13, v5 offset:396
	ds_read_b32 v14, v5 offset:528
	ds_read_b32 v15, v5 offset:660
	ds_read_b32 v16, v5 offset:792
	ds_read_b32 v17, v5 offset:924
	s_lshl_b64 s[0:1], s[0:1], 1
	s_add_u32 s0, s4, s0
	s_addc_u32 s1, s5, s1
	s_waitcnt lgkmcnt(6)
	v_cvt_pk_bf16_f32 v10, v10, v11
	s_waitcnt lgkmcnt(4)
	v_cvt_pk_bf16_f32 v11, v12, v13
	s_waitcnt lgkmcnt(2)
	v_cvt_pk_bf16_f32 v12, v14, v15
	v_or_b32_e32 v14, s9, v4
	v_lshl_add_u64 v[0:1], s[0:1], 0, v[160:161]
	v_mul_hi_i32_i24_e32 v15, s8, v14
	v_mul_i32_i24_e32 v14, s8, v14
	s_waitcnt lgkmcnt(0)
	v_cvt_pk_bf16_f32 v13, v16, v17
	v_lshl_add_u64 v[14:15], v[14:15], 1, v[0:1]
	global_store_dwordx4 v[14:15], v[10:13], off
	ds_read_b32 v10, v5 offset:32
	ds_read_b32 v11, v5 offset:164
	ds_read_b32 v12, v5 offset:296
	ds_read_b32 v13, v5 offset:428
	ds_read_b32 v14, v5 offset:560
	ds_read_b32 v15, v5 offset:692
	ds_read_b32 v16, v5 offset:824
	ds_read_b32 v17, v5 offset:956
	s_waitcnt lgkmcnt(0)
	v_cvt_pk_bf16_f32 v10, v10, v11
	v_cvt_pk_bf16_f32 v11, v12, v13
	v_cvt_pk_bf16_f32 v12, v14, v15
	v_or_b32_e32 v14, s9, v6
	v_mul_hi_i32_i24_e32 v15, s8, v14
	v_mul_i32_i24_e32 v14, s8, v14
	v_cvt_pk_bf16_f32 v13, v16, v17
	v_lshl_add_u64 v[14:15], v[14:15], 1, v[0:1]
	global_store_dwordx4 v[14:15], v[10:13], off
	ds_read_b32 v10, v5 offset:64
	ds_read_b32 v11, v5 offset:196
	ds_read_b32 v12, v5 offset:328
	ds_read_b32 v13, v5 offset:460
	ds_read_b32 v14, v5 offset:592
	ds_read_b32 v15, v5 offset:724
	ds_read_b32 v16, v5 offset:856
	ds_read_b32 v17, v5 offset:988
	s_waitcnt lgkmcnt(0)
	v_cvt_pk_bf16_f32 v10, v10, v11
	v_cvt_pk_bf16_f32 v11, v12, v13
	v_cvt_pk_bf16_f32 v12, v14, v15
	v_or_b32_e32 v14, s9, v7
	v_mul_hi_i32_i24_e32 v15, s8, v14
	v_mul_i32_i24_e32 v14, s8, v14
	v_cvt_pk_bf16_f32 v13, v16, v17
	v_lshl_add_u64 v[14:15], v[14:15], 1, v[0:1]
	global_store_dwordx4 v[14:15], v[10:13], off
	ds_read_b32 v10, v5 offset:96
	ds_read_b32 v11, v5 offset:228
	ds_read_b32 v12, v5 offset:360
	ds_read_b32 v13, v5 offset:492
	ds_read_b32 v14, v5 offset:624
	ds_read_b32 v15, v5 offset:756
	ds_read_b32 v16, v5 offset:888
	ds_read_b32 v17, v5 offset:1020
	s_waitcnt lgkmcnt(0)
	v_cvt_pk_bf16_f32 v10, v10, v11
	v_cvt_pk_bf16_f32 v11, v12, v13
	v_cvt_pk_bf16_f32 v12, v14, v15
	v_or_b32_e32 v14, s9, v8
	v_mul_hi_i32_i24_e32 v15, s8, v14
	v_mul_i32_i24_e32 v14, s8, v14
	s_add_i32 s19, s19, s12
	v_cvt_pk_bf16_f32 v13, v16, v17
	v_lshl_add_u64 v[0:1], v[14:15], 1, v[0:1]
	s_cmpk_gt_i32 s19, 0x4907
	global_store_dwordx4 v[0:1], v[10:13], off
	s_cbranch_scc0 .LBB0_585
	s_branch .LBB0_639
